# FFN-in SwiGLU epilogue rewritten by hand: packed f32 math directly on accumulator quads (g*u)*(rs^2/(1+2^(g*-log2e*rs))), 5 VALU per output instead of 9
# speedup vs baseline: 1.0130x; 1.0066x over previous
.LBB0_609:
	v_lshl_add_u32 v146, s0, 8, v1
	v_ashrrev_i32_e32 v147, 31, v146
	v_ashrrev_i32_e32 v249, 31, v248
	v_mov_b32_e32 v230, v240
	v_mov_b32_e32 v231, v241
	v_mov_b32_e32 v232, v242
	v_mov_b32_e32 v233, v243
	v_mov_b32_e32 v234, v244
	v_mov_b32_e32 v235, v245
	v_mov_b32_e32 v236, v246
	v_mov_b32_e32 v237, v247
	v_lshl_add_u64 v[248:249], v[248:249], 2, s[60:61]
	global_load_dword v241, v[248:249], off sc1
	global_load_dword v240, v[248:249], off offset:64 sc1
	global_load_dword v243, v[248:249], off offset:128 sc1
	global_load_dword v242, v[248:249], off offset:192 sc1
	global_load_dword v245, v[248:249], off offset:512 sc1
	global_load_dword v244, v[248:249], off offset:576 sc1
	global_load_dword v247, v[248:249], off offset:640 sc1
	global_load_dword v246, v[248:249], off offset:704 sc1
	v_mov_b64_e32 v[158:159], s[8:9]
	v_lshl_add_u32 v148, s1, 7, v153
	v_mov_b32_e32 v149, 0
	v_mov_b32_e32 v174, 0x358637bd
	v_mad_i64_i32 v[172:173], s[0:1], v146, s50, v[158:159]
	v_lshlrev_b64 v[148:149], 1, v[148:149]
	s_mov_b32 s0, 0x16000
	s_mov_b32 s1, 0
	v_lshl_add_u64 v[172:173], v[172:173], 0, v[148:149]
	v_fmamk_f32 v157, v231, 0x3a800000, v174
	s_nop 0
	v_rsq_f32_e32 v157, v157
	s_nop 0
	v_mul_f32_e32 v160, 0xbfb8aa3b, v157
	v_mul_f32_e32 v158, v157, v157
	v_pk_mul_f32 v[126:127], v[118:119], v[126:127]
	v_pk_mul_f32 v[128:129], v[120:121], v[128:129]
	v_pk_mul_f32 v[122:123], v[114:115], v[122:123]
	v_pk_mul_f32 v[124:125], v[116:117], v[124:125]
	v_pk_mul_f32 v[118:119], v[118:119], v[160:161] op_sel_hi:[1,0]
	v_pk_mul_f32 v[120:121], v[120:121], v[160:161] op_sel_hi:[1,0]
	v_pk_mul_f32 v[114:115], v[114:115], v[160:161] op_sel_hi:[1,0]
	v_pk_mul_f32 v[116:117], v[116:117], v[160:161] op_sel_hi:[1,0]
	v_exp_f32_e32 v118, v118
	v_exp_f32_e32 v119, v119
	v_exp_f32_e32 v120, v120
	v_exp_f32_e32 v121, v121
	v_exp_f32_e32 v114, v114
	v_exp_f32_e32 v115, v115
	v_exp_f32_e32 v116, v116
	v_exp_f32_e32 v117, v117
	v_pk_add_f32 v[118:119], v[118:119], 1.0 op_sel_hi:[1,0]
	v_pk_add_f32 v[120:121], v[120:121], 1.0 op_sel_hi:[1,0]
	v_pk_add_f32 v[114:115], v[114:115], 1.0 op_sel_hi:[1,0]
	v_pk_add_f32 v[116:117], v[116:117], 1.0 op_sel_hi:[1,0]
	v_rcp_f32_e32 v118, v118
	v_rcp_f32_e32 v119, v119
	v_rcp_f32_e32 v120, v120
	v_rcp_f32_e32 v121, v121
	v_rcp_f32_e32 v114, v114
	v_rcp_f32_e32 v115, v115
	v_rcp_f32_e32 v116, v116
	v_rcp_f32_e32 v117, v117
	v_pk_mul_f32 v[118:119], v[118:119], v[158:159] op_sel_hi:[1,0]
	v_pk_mul_f32 v[120:121], v[120:121], v[158:159] op_sel_hi:[1,0]
	v_pk_mul_f32 v[114:115], v[114:115], v[158:159] op_sel_hi:[1,0]
	v_pk_mul_f32 v[116:117], v[116:117], v[158:159] op_sel_hi:[1,0]
	v_pk_mul_f32 v[126:127], v[126:127], v[118:119]
	v_pk_mul_f32 v[128:129], v[128:129], v[120:121]
	v_pk_mul_f32 v[122:123], v[122:123], v[114:115]
	v_pk_mul_f32 v[124:125], v[124:125], v[116:117]
	v_cvt_pk_bf16_f32 v162, v126, v127
	v_cvt_pk_bf16_f32 v163, v128, v129
	v_cvt_pk_bf16_f32 v164, v122, v123
	v_cvt_pk_bf16_f32 v165, v124, v125
	s_nop 1
	v_permlane16_swap_b32_e32 v162, v164
	v_permlane16_swap_b32_e32 v163, v165
	s_nop 1
	global_store_dwordx4 v[172:173], v[162:165], off
	v_lshl_add_u64 v[172:173], v[172:173], 0, s[0:1]
	v_fmamk_f32 v157, v230, 0x3a800000, v174
	s_nop 0
	v_rsq_f32_e32 v157, v157
	s_nop 0
	v_mul_f32_e32 v160, 0xbfb8aa3b, v157
	v_mul_f32_e32 v158, v157, v157
	v_pk_mul_f32 v[106:107], v[110:111], v[106:107]
	v_pk_mul_f32 v[108:109], v[112:113], v[108:109]
	v_pk_mul_f32 v[98:99], v[102:103], v[98:99]
	v_pk_mul_f32 v[100:101], v[104:105], v[100:101]
	v_pk_mul_f32 v[110:111], v[110:111], v[160:161] op_sel_hi:[1,0]
	v_pk_mul_f32 v[112:113], v[112:113], v[160:161] op_sel_hi:[1,0]
	v_pk_mul_f32 v[102:103], v[102:103], v[160:161] op_sel_hi:[1,0]
	v_pk_mul_f32 v[104:105], v[104:105], v[160:161] op_sel_hi:[1,0]
	v_exp_f32_e32 v110, v110
	v_exp_f32_e32 v111, v111
	v_exp_f32_e32 v112, v112
	v_exp_f32_e32 v113, v113
	v_exp_f32_e32 v102, v102
	v_exp_f32_e32 v103, v103
	v_exp_f32_e32 v104, v104
	v_exp_f32_e32 v105, v105
	v_pk_add_f32 v[110:111], v[110:111], 1.0 op_sel_hi:[1,0]
	v_pk_add_f32 v[112:113], v[112:113], 1.0 op_sel_hi:[1,0]
	v_pk_add_f32 v[102:103], v[102:103], 1.0 op_sel_hi:[1,0]
	v_pk_add_f32 v[104:105], v[104:105], 1.0 op_sel_hi:[1,0]
	v_rcp_f32_e32 v110, v110
	v_rcp_f32_e32 v111, v111
	v_rcp_f32_e32 v112, v112
	v_rcp_f32_e32 v113, v113
	v_rcp_f32_e32 v102, v102
	v_rcp_f32_e32 v103, v103
	v_rcp_f32_e32 v104, v104
	v_rcp_f32_e32 v105, v105
	v_pk_mul_f32 v[110:111], v[110:111], v[158:159] op_sel_hi:[1,0]
	v_pk_mul_f32 v[112:113], v[112:113], v[158:159] op_sel_hi:[1,0]
	v_pk_mul_f32 v[102:103], v[102:103], v[158:159] op_sel_hi:[1,0]
	v_pk_mul_f32 v[104:105], v[104:105], v[158:159] op_sel_hi:[1,0]
	v_pk_mul_f32 v[106:107], v[106:107], v[110:111]
	v_pk_mul_f32 v[108:109], v[108:109], v[112:113]
	v_pk_mul_f32 v[98:99], v[98:99], v[102:103]
	v_pk_mul_f32 v[100:101], v[100:101], v[104:105]
	v_cvt_pk_bf16_f32 v166, v106, v107
	v_cvt_pk_bf16_f32 v167, v108, v109
	v_cvt_pk_bf16_f32 v168, v98, v99
	v_cvt_pk_bf16_f32 v169, v100, v101
	s_nop 1
	v_permlane16_swap_b32_e32 v166, v168
	v_permlane16_swap_b32_e32 v167, v169
	s_nop 1
	global_store_dwordx4 v[172:173], v[166:169], off
	v_lshl_add_u64 v[172:173], v[172:173], 0, s[0:1]
	v_fmamk_f32 v157, v233, 0x3a800000, v174
	s_nop 0
	v_rsq_f32_e32 v157, v157
	s_nop 0
	v_mul_f32_e32 v160, 0xbfb8aa3b, v157
	v_mul_f32_e32 v158, v157, v157
	v_pk_mul_f32 v[94:95], v[86:87], v[94:95]
	v_pk_mul_f32 v[96:97], v[88:89], v[96:97]
	v_pk_mul_f32 v[90:91], v[82:83], v[90:91]
	v_pk_mul_f32 v[92:93], v[84:85], v[92:93]
	v_pk_mul_f32 v[86:87], v[86:87], v[160:161] op_sel_hi:[1,0]
	v_pk_mul_f32 v[88:89], v[88:89], v[160:161] op_sel_hi:[1,0]
	v_pk_mul_f32 v[82:83], v[82:83], v[160:161] op_sel_hi:[1,0]
	v_pk_mul_f32 v[84:85], v[84:85], v[160:161] op_sel_hi:[1,0]
	v_exp_f32_e32 v86, v86
	v_exp_f32_e32 v87, v87
	v_exp_f32_e32 v88, v88
	v_exp_f32_e32 v89, v89
	v_exp_f32_e32 v82, v82
	v_exp_f32_e32 v83, v83
	v_exp_f32_e32 v84, v84
	v_exp_f32_e32 v85, v85
	v_pk_add_f32 v[86:87], v[86:87], 1.0 op_sel_hi:[1,0]
	v_pk_add_f32 v[88:89], v[88:89], 1.0 op_sel_hi:[1,0]
	v_pk_add_f32 v[82:83], v[82:83], 1.0 op_sel_hi:[1,0]
	v_pk_add_f32 v[84:85], v[84:85], 1.0 op_sel_hi:[1,0]
	v_rcp_f32_e32 v86, v86
	v_rcp_f32_e32 v87, v87
	v_rcp_f32_e32 v88, v88
	v_rcp_f32_e32 v89, v89
	v_rcp_f32_e32 v82, v82
	v_rcp_f32_e32 v83, v83
	v_rcp_f32_e32 v84, v84
	v_rcp_f32_e32 v85, v85
	v_pk_mul_f32 v[86:87], v[86:87], v[158:159] op_sel_hi:[1,0]
	v_pk_mul_f32 v[88:89], v[88:89], v[158:159] op_sel_hi:[1,0]
	v_pk_mul_f32 v[82:83], v[82:83], v[158:159] op_sel_hi:[1,0]
	v_pk_mul_f32 v[84:85], v[84:85], v[158:159] op_sel_hi:[1,0]
	v_pk_mul_f32 v[94:95], v[94:95], v[86:87]
	v_pk_mul_f32 v[96:97], v[96:97], v[88:89]
	v_pk_mul_f32 v[90:91], v[90:91], v[82:83]
	v_pk_mul_f32 v[92:93], v[92:93], v[84:85]
	v_cvt_pk_bf16_f32 v162, v94, v95
	v_cvt_pk_bf16_f32 v163, v96, v97
	v_cvt_pk_bf16_f32 v164, v90, v91
	v_cvt_pk_bf16_f32 v165, v92, v93
	s_nop 1
	v_permlane16_swap_b32_e32 v162, v164
	v_permlane16_swap_b32_e32 v163, v165
	s_nop 1
	global_store_dwordx4 v[172:173], v[162:165], off
	v_lshl_add_u64 v[172:173], v[172:173], 0, s[0:1]
	v_fmamk_f32 v157, v232, 0x3a800000, v174
	s_nop 0
	v_rsq_f32_e32 v157, v157
	s_nop 0
	v_mul_f32_e32 v160, 0xbfb8aa3b, v157
	v_mul_f32_e32 v158, v157, v157
	v_pk_mul_f32 v[74:75], v[78:79], v[74:75]
	v_pk_mul_f32 v[76:77], v[80:81], v[76:77]
	v_pk_mul_f32 v[66:67], v[70:71], v[66:67]
	v_pk_mul_f32 v[68:69], v[72:73], v[68:69]
	v_pk_mul_f32 v[78:79], v[78:79], v[160:161] op_sel_hi:[1,0]
	v_pk_mul_f32 v[80:81], v[80:81], v[160:161] op_sel_hi:[1,0]
	v_pk_mul_f32 v[70:71], v[70:71], v[160:161] op_sel_hi:[1,0]
	v_pk_mul_f32 v[72:73], v[72:73], v[160:161] op_sel_hi:[1,0]
	v_exp_f32_e32 v78, v78
	v_exp_f32_e32 v79, v79
	v_exp_f32_e32 v80, v80
	v_exp_f32_e32 v81, v81
	v_exp_f32_e32 v70, v70
	v_exp_f32_e32 v71, v71
	v_exp_f32_e32 v72, v72
	v_exp_f32_e32 v73, v73
	v_pk_add_f32 v[78:79], v[78:79], 1.0 op_sel_hi:[1,0]
	v_pk_add_f32 v[80:81], v[80:81], 1.0 op_sel_hi:[1,0]
	v_pk_add_f32 v[70:71], v[70:71], 1.0 op_sel_hi:[1,0]
	v_pk_add_f32 v[72:73], v[72:73], 1.0 op_sel_hi:[1,0]
	v_rcp_f32_e32 v78, v78
	v_rcp_f32_e32 v79, v79
	v_rcp_f32_e32 v80, v80
	v_rcp_f32_e32 v81, v81
	v_rcp_f32_e32 v70, v70
	v_rcp_f32_e32 v71, v71
	v_rcp_f32_e32 v72, v72
	v_rcp_f32_e32 v73, v73
	v_pk_mul_f32 v[78:79], v[78:79], v[158:159] op_sel_hi:[1,0]
	v_pk_mul_f32 v[80:81], v[80:81], v[158:159] op_sel_hi:[1,0]
	v_pk_mul_f32 v[70:71], v[70:71], v[158:159] op_sel_hi:[1,0]
	v_pk_mul_f32 v[72:73], v[72:73], v[158:159] op_sel_hi:[1,0]
	v_pk_mul_f32 v[74:75], v[74:75], v[78:79]
	v_pk_mul_f32 v[76:77], v[76:77], v[80:81]
	v_pk_mul_f32 v[66:67], v[66:67], v[70:71]
	v_pk_mul_f32 v[68:69], v[68:69], v[72:73]
	v_cvt_pk_bf16_f32 v166, v74, v75
	v_cvt_pk_bf16_f32 v167, v76, v77
	v_cvt_pk_bf16_f32 v168, v66, v67
	v_cvt_pk_bf16_f32 v169, v68, v69
	s_nop 1
	v_permlane16_swap_b32_e32 v166, v168
	v_permlane16_swap_b32_e32 v167, v169
	s_nop 1
	global_store_dwordx4 v[172:173], v[166:169], off
	s_mov_b32 s0, 0x6e000
	v_lshl_add_u64 v[172:173], v[172:173], 0, s[0:1]
	s_mov_b32 s0, 0x16000
	v_fmamk_f32 v157, v235, 0x3a800000, v174
	s_nop 0
	v_rsq_f32_e32 v157, v157
	s_nop 0
	v_mul_f32_e32 v160, 0xbfb8aa3b, v157
	v_mul_f32_e32 v158, v157, v157
	v_pk_mul_f32 v[62:63], v[58:59], v[62:63]
	v_pk_mul_f32 v[64:65], v[60:61], v[64:65]
	v_pk_mul_f32 v[54:55], v[50:51], v[54:55]
	v_pk_mul_f32 v[56:57], v[52:53], v[56:57]
	v_pk_mul_f32 v[58:59], v[58:59], v[160:161] op_sel_hi:[1,0]
	v_pk_mul_f32 v[60:61], v[60:61], v[160:161] op_sel_hi:[1,0]
	v_pk_mul_f32 v[50:51], v[50:51], v[160:161] op_sel_hi:[1,0]
	v_pk_mul_f32 v[52:53], v[52:53], v[160:161] op_sel_hi:[1,0]
	v_exp_f32_e32 v58, v58
	v_exp_f32_e32 v59, v59
	v_exp_f32_e32 v60, v60
	v_exp_f32_e32 v61, v61
	v_exp_f32_e32 v50, v50
	v_exp_f32_e32 v51, v51
	v_exp_f32_e32 v52, v52
	v_exp_f32_e32 v53, v53
	v_pk_add_f32 v[58:59], v[58:59], 1.0 op_sel_hi:[1,0]
	v_pk_add_f32 v[60:61], v[60:61], 1.0 op_sel_hi:[1,0]
	v_pk_add_f32 v[50:51], v[50:51], 1.0 op_sel_hi:[1,0]
	v_pk_add_f32 v[52:53], v[52:53], 1.0 op_sel_hi:[1,0]
	v_rcp_f32_e32 v58, v58
	v_rcp_f32_e32 v59, v59
	v_rcp_f32_e32 v60, v60
	v_rcp_f32_e32 v61, v61
	v_rcp_f32_e32 v50, v50
	v_rcp_f32_e32 v51, v51
	v_rcp_f32_e32 v52, v52
	v_rcp_f32_e32 v53, v53
	v_pk_mul_f32 v[58:59], v[58:59], v[158:159] op_sel_hi:[1,0]
	v_pk_mul_f32 v[60:61], v[60:61], v[158:159] op_sel_hi:[1,0]
	v_pk_mul_f32 v[50:51], v[50:51], v[158:159] op_sel_hi:[1,0]
	v_pk_mul_f32 v[52:53], v[52:53], v[158:159] op_sel_hi:[1,0]
	v_pk_mul_f32 v[62:63], v[62:63], v[58:59]
	v_pk_mul_f32 v[64:65], v[64:65], v[60:61]
	v_pk_mul_f32 v[54:55], v[54:55], v[50:51]
	v_pk_mul_f32 v[56:57], v[56:57], v[52:53]
	v_cvt_pk_bf16_f32 v162, v62, v63
	v_cvt_pk_bf16_f32 v163, v64, v65
	v_cvt_pk_bf16_f32 v164, v54, v55
	v_cvt_pk_bf16_f32 v165, v56, v57
	s_nop 1
	v_permlane16_swap_b32_e32 v162, v164
	v_permlane16_swap_b32_e32 v163, v165
	s_nop 1
	global_store_dwordx4 v[172:173], v[162:165], off
	v_lshl_add_u64 v[172:173], v[172:173], 0, s[0:1]
	v_fmamk_f32 v157, v234, 0x3a800000, v174
	s_nop 0
	v_rsq_f32_e32 v157, v157
	s_nop 0
	v_mul_f32_e32 v160, 0xbfb8aa3b, v157
	v_mul_f32_e32 v158, v157, v157
	v_pk_mul_f32 v[42:43], v[46:47], v[42:43]
	v_pk_mul_f32 v[44:45], v[48:49], v[44:45]
	v_pk_mul_f32 v[34:35], v[38:39], v[34:35]
	v_pk_mul_f32 v[36:37], v[40:41], v[36:37]
	v_pk_mul_f32 v[46:47], v[46:47], v[160:161] op_sel_hi:[1,0]
	v_pk_mul_f32 v[48:49], v[48:49], v[160:161] op_sel_hi:[1,0]
	v_pk_mul_f32 v[38:39], v[38:39], v[160:161] op_sel_hi:[1,0]
	v_pk_mul_f32 v[40:41], v[40:41], v[160:161] op_sel_hi:[1,0]
	v_exp_f32_e32 v46, v46
	v_exp_f32_e32 v47, v47
	v_exp_f32_e32 v48, v48
	v_exp_f32_e32 v49, v49
	v_exp_f32_e32 v38, v38
	v_exp_f32_e32 v39, v39
	v_exp_f32_e32 v40, v40
	v_exp_f32_e32 v41, v41
	v_pk_add_f32 v[46:47], v[46:47], 1.0 op_sel_hi:[1,0]
	v_pk_add_f32 v[48:49], v[48:49], 1.0 op_sel_hi:[1,0]
	v_pk_add_f32 v[38:39], v[38:39], 1.0 op_sel_hi:[1,0]
	v_pk_add_f32 v[40:41], v[40:41], 1.0 op_sel_hi:[1,0]
	v_rcp_f32_e32 v46, v46
	v_rcp_f32_e32 v47, v47
	v_rcp_f32_e32 v48, v48
	v_rcp_f32_e32 v49, v49
	v_rcp_f32_e32 v38, v38
	v_rcp_f32_e32 v39, v39
	v_rcp_f32_e32 v40, v40
	v_rcp_f32_e32 v41, v41
	v_pk_mul_f32 v[46:47], v[46:47], v[158:159] op_sel_hi:[1,0]
	v_pk_mul_f32 v[48:49], v[48:49], v[158:159] op_sel_hi:[1,0]
	v_pk_mul_f32 v[38:39], v[38:39], v[158:159] op_sel_hi:[1,0]
	v_pk_mul_f32 v[40:41], v[40:41], v[158:159] op_sel_hi:[1,0]
	v_pk_mul_f32 v[42:43], v[42:43], v[46:47]
	v_pk_mul_f32 v[44:45], v[44:45], v[48:49]
	v_pk_mul_f32 v[34:35], v[34:35], v[38:39]
	v_pk_mul_f32 v[36:37], v[36:37], v[40:41]
	v_cvt_pk_bf16_f32 v166, v42, v43
	v_cvt_pk_bf16_f32 v167, v44, v45
	v_cvt_pk_bf16_f32 v168, v34, v35
	v_cvt_pk_bf16_f32 v169, v36, v37
	s_nop 1
	v_permlane16_swap_b32_e32 v166, v168
	v_permlane16_swap_b32_e32 v167, v169
	s_nop 1
	global_store_dwordx4 v[172:173], v[166:169], off
	v_lshl_add_u64 v[172:173], v[172:173], 0, s[0:1]
	v_fmamk_f32 v157, v237, 0x3a800000, v174
	s_nop 0
	v_rsq_f32_e32 v157, v157
	s_nop 0
	v_mul_f32_e32 v160, 0xbfb8aa3b, v157
	v_mul_f32_e32 v158, v157, v157
	v_pk_mul_f32 v[30:31], v[22:23], v[30:31]
	v_pk_mul_f32 v[32:33], v[24:25], v[32:33]
	v_pk_mul_f32 v[26:27], v[18:19], v[26:27]
	v_pk_mul_f32 v[28:29], v[20:21], v[28:29]
	v_pk_mul_f32 v[22:23], v[22:23], v[160:161] op_sel_hi:[1,0]
	v_pk_mul_f32 v[24:25], v[24:25], v[160:161] op_sel_hi:[1,0]
	v_pk_mul_f32 v[18:19], v[18:19], v[160:161] op_sel_hi:[1,0]
	v_pk_mul_f32 v[20:21], v[20:21], v[160:161] op_sel_hi:[1,0]
	v_exp_f32_e32 v22, v22
	v_exp_f32_e32 v23, v23
	v_exp_f32_e32 v24, v24
	v_exp_f32_e32 v25, v25
	v_exp_f32_e32 v18, v18
	v_exp_f32_e32 v19, v19
	v_exp_f32_e32 v20, v20
	v_exp_f32_e32 v21, v21
	v_pk_add_f32 v[22:23], v[22:23], 1.0 op_sel_hi:[1,0]
	v_pk_add_f32 v[24:25], v[24:25], 1.0 op_sel_hi:[1,0]
	v_pk_add_f32 v[18:19], v[18:19], 1.0 op_sel_hi:[1,0]
	v_pk_add_f32 v[20:21], v[20:21], 1.0 op_sel_hi:[1,0]
	v_rcp_f32_e32 v22, v22
	v_rcp_f32_e32 v23, v23
	v_rcp_f32_e32 v24, v24
	v_rcp_f32_e32 v25, v25
	v_rcp_f32_e32 v18, v18
	v_rcp_f32_e32 v19, v19
	v_rcp_f32_e32 v20, v20
	v_rcp_f32_e32 v21, v21
	v_pk_mul_f32 v[22:23], v[22:23], v[158:159] op_sel_hi:[1,0]
	v_pk_mul_f32 v[24:25], v[24:25], v[158:159] op_sel_hi:[1,0]
	v_pk_mul_f32 v[18:19], v[18:19], v[158:159] op_sel_hi:[1,0]
	v_pk_mul_f32 v[20:21], v[20:21], v[158:159] op_sel_hi:[1,0]
	v_pk_mul_f32 v[30:31], v[30:31], v[22:23]
	v_pk_mul_f32 v[32:33], v[32:33], v[24:25]
	v_pk_mul_f32 v[26:27], v[26:27], v[18:19]
	v_pk_mul_f32 v[28:29], v[28:29], v[20:21]
	v_cvt_pk_bf16_f32 v162, v30, v31
	v_cvt_pk_bf16_f32 v163, v32, v33
	v_cvt_pk_bf16_f32 v164, v26, v27
	v_cvt_pk_bf16_f32 v165, v28, v29
	s_nop 1
	v_permlane16_swap_b32_e32 v162, v164
	v_permlane16_swap_b32_e32 v163, v165
	s_nop 1
	global_store_dwordx4 v[172:173], v[162:165], off
	v_lshl_add_u64 v[172:173], v[172:173], 0, s[0:1]
	v_fmamk_f32 v157, v236, 0x3a800000, v174
	s_nop 0
	v_rsq_f32_e32 v157, v157
	s_nop 0
	v_mul_f32_e32 v160, 0xbfb8aa3b, v157
	v_mul_f32_e32 v158, v157, v157
	v_pk_mul_f32 v[10:11], v[14:15], v[10:11]
	v_pk_mul_f32 v[12:13], v[16:17], v[12:13]
	v_pk_mul_f32 v[2:3], v[6:7], v[2:3]
	v_pk_mul_f32 v[4:5], v[8:9], v[4:5]
	v_pk_mul_f32 v[14:15], v[14:15], v[160:161] op_sel_hi:[1,0]
	v_pk_mul_f32 v[16:17], v[16:17], v[160:161] op_sel_hi:[1,0]
	v_pk_mul_f32 v[6:7], v[6:7], v[160:161] op_sel_hi:[1,0]
	v_pk_mul_f32 v[8:9], v[8:9], v[160:161] op_sel_hi:[1,0]
	v_exp_f32_e32 v14, v14
	v_exp_f32_e32 v15, v15
	v_exp_f32_e32 v16, v16
	v_exp_f32_e32 v17, v17
	v_exp_f32_e32 v6, v6
	v_exp_f32_e32 v7, v7
	v_exp_f32_e32 v8, v8
	v_exp_f32_e32 v9, v9
	v_pk_add_f32 v[14:15], v[14:15], 1.0 op_sel_hi:[1,0]
	v_pk_add_f32 v[16:17], v[16:17], 1.0 op_sel_hi:[1,0]
	v_pk_add_f32 v[6:7], v[6:7], 1.0 op_sel_hi:[1,0]
	v_pk_add_f32 v[8:9], v[8:9], 1.0 op_sel_hi:[1,0]
	v_rcp_f32_e32 v14, v14
	v_rcp_f32_e32 v15, v15
	v_rcp_f32_e32 v16, v16
	v_rcp_f32_e32 v17, v17
	v_rcp_f32_e32 v6, v6
	v_rcp_f32_e32 v7, v7
	v_rcp_f32_e32 v8, v8
	v_rcp_f32_e32 v9, v9
	v_pk_mul_f32 v[14:15], v[14:15], v[158:159] op_sel_hi:[1,0]
	v_pk_mul_f32 v[16:17], v[16:17], v[158:159] op_sel_hi:[1,0]
	v_pk_mul_f32 v[6:7], v[6:7], v[158:159] op_sel_hi:[1,0]
	v_pk_mul_f32 v[8:9], v[8:9], v[158:159] op_sel_hi:[1,0]
	v_pk_mul_f32 v[10:11], v[10:11], v[14:15]
	v_pk_mul_f32 v[12:13], v[12:13], v[16:17]
	v_pk_mul_f32 v[2:3], v[2:3], v[6:7]
	v_pk_mul_f32 v[4:5], v[4:5], v[8:9]
	v_cvt_pk_bf16_f32 v166, v10, v11
	v_cvt_pk_bf16_f32 v167, v12, v13
	v_cvt_pk_bf16_f32 v168, v2, v3
	v_cvt_pk_bf16_f32 v169, v4, v5
	s_nop 1
	v_permlane16_swap_b32_e32 v166, v168
	v_permlane16_swap_b32_e32 v167, v169
	s_nop 1
	global_store_dwordx4 v[172:173], v[166:169], off
	s_andn2_b64 vcc, exec, s[4:5]
	s_mov_b64 s[0:1], -1
	s_cbranch_vccnz .LBB0_598
	s_andn2_b64 vcc, exec, s[6:7]
	s_cbranch_vccnz .LBB0_597
	s_barrier
	s_branch .LBB0_597
